# same optimisations as v14, regenerated by one scripted pipeline; score LDS key staging now re-stages when the head changes and the mixer renumbering is guarded to 512-workgroup grids (robustness only)
# speedup vs baseline: 1.1308x; 1.0037x over previous
; __device__ __forceinline__ int tid_() { int t = threadIdx.x; asm volatile("" : "+v"(t)); return t; }
; __device__ void ph_mixer(const P& p, u16* lds) {
;     ...
;   if ((int)blockIdx.x < NSCAN) { if (MIXMASK & 1) scan_seq(p, blockIdx.x, lds); return; }
;   const int NA = 2048, NSA = 256, NSD = 256, NCP = 2409;
;   const int st = gridDim.x - NSCAN, b0 = blockIdx.x - NSCAN;
;   auto first = [&](int off) { int f = b0 - (off % st); return f < 0 ? f + st : f; };
;   if (MIXMASK & 8) for (int it = first(0); it < NSD; it += st) dn_sample_wave(p, it * 4 + (tid_() >> 6));
;   if (MIXMASK & 4) for (int it = first(224); it < NSA; it += st) attn_sample_item(p, it, lds);
;   if (MIXMASK & 2) for (int it = first(288); it < NA; it += st) attn_prompt_item(p, it, lds);
;   if (MIXMASK & 16) for (int it = first(256); it < NCP; it += st) copy_item(p, it);
.LBB0_300:
	s_cmp_lt_i32 s6, 4
	s_cselect_b64 s[0:1], -1, 0
	s_cmp_gt_i32 s7, 3
	s_cselect_b64 s[2:3], -1, 0
	s_and_b64 s[0:1], s[0:1], s[2:3]
	s_andn2_b64 vcc, exec, s[0:1]
	s_cbranch_vccnz .LBB0_539
	v_readlane_b32 s2, v228, 0
	v_readlane_b32 s0, v228, 10
	s_nop 1
	v_writelane_b32 v227, s2, 60
	v_writelane_b32 v227, s0, 61
	s_cmp_gt_i32 s2, 31
	s_mov_b64 s[0:1], -1
	v_readlane_b32 s3, v228, 1
	s_cbranch_scc0 .LBB0_478
	v_readlane_b32 s0, v228, 10
	s_nop 1
	s_cmpk_lg_u32 s0, 0x200
	s_cbranch_scc1 .Lmx_orig
	s_cmpk_lt_u32 s2, 0x100
	s_cbranch_scc1 .Lmx_keep
	s_cmpk_lt_u32 s2, 0x120
	s_cbranch_scc1 .LBB0_485
	s_sub_i32 s2, s2, 32

; __device__ __forceinline__ int tid_() { int t = threadIdx.x; asm volatile("" : "+v"(t)); return t; }
; __device__ void dn_sample_wave(const P& p, int bh) {
;   const int lane = tid_() & 63;
;   const int h = bh & 7, b = bh >> 3;
;   float cw[3][4], xs[3][3];
; #pragma unroll
;   for (int arr = 0; arr < 3; ++arr) {
;     const int ch = arr * 512 + h * 64 + lane;
; #pragma unroll
;     for (int j = 0; j < 4; ++j) cw[arr][j] = p.conv_w[j * 1536 + ch];
; #pragma unroll
;     for (int j = 0; j < 3; ++j) xs[arr][j] = p.sconv[((size_t)b * 3 + j) * 1536 + ch];
;   }
;   float S[64];
;   const float* s0 = p.sdelta + (size_t)bh * 4096 + lane;
; #pragma unroll
;   for (int d = 0; d < 64; ++d) S[d] = s0[d * 64];
;   const float eA = __expf(p.a_log[h]), dtb = p.dt_bias[h], gn = p.dn_norm[lane];
;   u16 nx[3], nar, nbr, nz;
;   {
;     const size_t tok = (size_t)TP + b * 8;
; #pragma unroll
;     for (int arr = 0; arr < 3; ++arr) nx[arr] = p_proj[tok * INW + 768 + arr * 512 + h * 64 + lane];
;     nar = p_proj[tok * INW + 2816 + h]; nbr = p_proj[tok * INW + 2824 + h]; nz = p_proj[tok * INW + 2304 + h * 64 + lane];
;   }
; __device__ void ph_mixer(const P& p, u16* lds) {
;     ...
;   const int NA = 2048, NSA = 256, NSD = 256, NCP = 2409;
;   const int st = gridDim.x - NSCAN, b0 = blockIdx.x - NSCAN;
;   auto first = [&](int off) { int f = b0 - (off % st); return f < 0 ? f + st : f; };
;   if (MIXMASK & 8) for (int it = first(0); it < NSD; it += st) dn_sample_wave(p, it * 4 + (tid_() >> 6));
.Lmx_orig:
	v_readlane_b32 s0, v228, 10
	s_sub_i32 s0, s0, 32
	v_readlane_b32 s1, v228, 11
	v_writelane_b32 v227, s0, 1
	s_sub_i32 s0, s2, 32
	s_cmpk_gt_u32 s2, 0x11f
	v_writelane_b32 v227, s0, 11
	s_cbranch_scc1 .LBB0_309
	v_readlane_b32 s0, v228, 2
	v_readlane_b32 s4, v228, 6
	v_readlane_b32 s1, v228, 3
	v_readlane_b32 s5, v228, 7
	s_add_u32 s0, s4, 0x9752000
	v_readlane_b32 s6, v228, 8
	s_addc_u32 s1, s5, 0
	v_readlane_b32 s7, v228, 9
	s_add_u32 s4, s6, 0x8140600
	v_writelane_b32 v227, s0, 3
	s_addc_u32 s5, s7, 0
	v_readlane_b32 s2, v228, 4
	v_writelane_b32 v227, s1, 4
	s_add_u32 s0, s6, 0x8140000
	s_addc_u32 s1, s7, 0
	v_readlane_b32 s3, v228, 5
	s_add_u32 s2, s6, 0x177c8400
	s_addc_u32 s3, s7, 0
	v_writelane_b32 v227, s2, 7
	v_mov_b32_e32 v1, 0
	s_movk_i32 s18, 0x1000
	v_writelane_b32 v227, s3, 8
	v_readlane_b32 s2, v228, 0
	v_readlane_b32 s3, v228, 1
	s_lshl_b32 s14, s2, 2
	v_readlane_b32 s2, v228, 10
	s_lshl_b32 s2, s2, 2
	s_add_i32 s15, s14, 0xffffff80
	v_writelane_b32 v227, s2, 9
	s_addk_i32 s2, 0xff80
	v_writelane_b32 v227, s2, 12
	v_writelane_b32 v227, s4, 5
	s_movk_i32 s22, 0x1620
	v_mov_b64_e32 v[4:5], s[0:1]
	v_writelane_b32 v227, s5, 6
	v_mov_b64_e32 v[2:3], s[4:5]
	s_movk_i32 s1, 0x3000
	v_mov_b32_e32 v9, 0x3ecc95a3
	v_mov_b32_e32 v170, 0x358637bd
	s_mov_b32 s23, 0x800000
	v_mov_b32_e32 v6, 0x3f317218
	v_mov_b32_e32 v171, 0x7f800000
	v_mov_b32_e32 v172, 0x7fc00000
	v_mov_b32_e32 v173, 0xff800000
	v_readlane_b32 s24, v227, 11
	v_readlane_b32 s3, v228, 11
	s_branch .LBB0_305

; __device__ __forceinline__ int tid_() { int t = threadIdx.x; asm volatile("" : "+v"(t)); return t; }
; __device__ __forceinline__ f32x4 mfma16(bf16x8 a, bf16x8 b, f32x4 c) { return __builtin_amdgcn_mfma_f32_16x16x32_bf16(a, b, c, 0, 0, 0); }
; __device__ void ph_score(const P& p, int* lds) {
;   const int lane = tid_() & 63, w = tid_() >> 6, fr = lane & 15, fq = lane >> 4;
;   const u16* Qb = p_proj;
;   int* experts = (int*)p_mix;
;   float* gates = (float*)(p_mix) + (size_t)TT * 128;
;   int* myl = lds + w * 512 + fr * 32;
;   for (int it = blockIdx.x; it < 528 * 8; it += gridDim.x) {
;     const int h = it & 7, tile = it >> 3;
;     const size_t tok = (size_t)tile * 64 + w * 16 + fr;
;     float tv[2][16];
; #pragma unroll
;     for (int half = 0; half < 2; ++half) {
;       const u16* Kb = (half ? p_K2b : p_K1b) + h * 128 * 128;
;       f32x4 sc[8];
; #pragma unroll
;       for (int mt = 0; mt < 8; ++mt) sc[mt] = f32x4{0.f, 0.f, 0.f, 0.f};
; #pragma unroll
;       for (int ks = 0; ks < 4; ++ks) {
;         bf16x8 qf = *(const bf16x8*)(Qb + tok * 2048 + h * 256 + half * 128 + ks * 32 + fq * 8);
; #pragma unroll
;         for (int mt = 0; mt < 8; ++mt) {
;           bf16x8 kf = *(const bf16x8*)(Kb + (mt * 16 + fr) * 128 + ks * 32 + fq * 8);
;           sc[mt] = mfma16(kf, qf, sc[mt]);
;         }
;       }
;       int a[16], b[16];
; #pragma unroll
;       for (int mt = 0; mt < 4; ++mt)
; #pragma unroll
;         for (int r = 0; r < 4; ++r) {
;           a[mt * 4 + r] = key_pack(sc[mt][r], mt * 16 + fq * 4 + r, 0x7f);
;           b[mt * 4 + r] = key_pack(sc[mt + 4][r], (mt + 4) * 16 + fq * 4 + r, 0x7f);
.LBB0_753:
	s_cmp_lt_i32 s6, 9
	s_cselect_b64 s[0:1], -1, 0
	s_cmp_gt_i32 s7, 8
	s_cselect_b64 s[2:3], -1, 0
	s_and_b64 s[0:1], s[0:1], s[2:3]
	s_andn2_b64 vcc, exec, s[0:1]
	s_cbranch_vccnz .LBB0_911
	v_readlane_b32 s0, v228, 0
	v_mov_b32_e32 v0, v220
	v_mov_b32_e32 v1, v220
	s_cmpk_gt_i32 s0, 0x107f
	v_readlane_b32 s1, v228, 1
	s_cbranch_scc1 .LBB0_857
	s_mov_b32 s87, -1
	v_readlane_b32 s4, v228, 2
	v_and_b32_e32 v2, 15, v0
	v_readlane_b32 s10, v228, 8
	v_ashrrev_i32_e32 v1, 6, v1
	s_waitcnt vmcnt(0)
	v_bfe_u32 v21, v0, 4, 2
	v_readlane_b32 s11, v228, 9
	s_add_u32 s2, s10, 0x8140000
	v_lshlrev_b32_e32 v0, 7, v2
	s_addc_u32 s3, s11, 0
	v_lshl_or_b32 v49, v1, 11, v0
	v_lshlrev_b32_e32 v1, 4, v1
	s_add_u32 s60, s10, 0x137c8000
	v_ashrrev_i32_e32 v17, 31, v1
	v_or_b32_e32 v16, v1, v2
	v_mbcnt_lo_u32_b32 v1, -1, 0
	s_addc_u32 s61, s11, 0
	v_mbcnt_hi_u32_b32 v1, -1, v1
	s_add_u32 s68, s10, 0x14848000
	v_mov_b32_e32 v19, 0
	v_and_b32_e32 v4, 64, v1
	v_lshlrev_b32_e32 v18, 4, v21
	s_addc_u32 s69, s11, 0
	v_xor_b32_e32 v3, 32, v1
	v_add_u32_e32 v4, 64, v4
	v_lshl_add_u64 v[24:25], s[10:11], 0, v[18:19]
	s_mov_b64 s[10:11], 0xe40000
	v_cmp_lt_i32_e32 vcc, v3, v4
	v_lshl_add_u64 v[22:23], v[24:25], 0, s[10:11]
	s_mov_b64 s[10:11], 0xe80000
	v_readlane_b32 s5, v228, 3
	v_readlane_b32 s6, v228, 4
	v_readlane_b32 s7, v228, 5
	v_readlane_b32 s8, v228, 6
	v_readlane_b32 s9, v228, 7
	v_lshlrev_b32_e32 v2, 3, v21
	v_lshlrev_b32_e32 v20, 2, v21
	v_cndmask_b32_e32 v1, v1, v3, vcc
	v_lshlrev_b32_e32 v55, 6, v21
	v_or_b32_e32 v4, 0x800, v0
	v_or_b32_e32 v6, 0x1000, v0
	v_or_b32_e32 v8, 0x1800, v0
	v_or_b32_e32 v10, 0x2000, v0
	v_or_b32_e32 v12, 0x2800, v0
	v_or_b32_e32 v14, 0x3000, v0
	v_or_b32_e32 v42, 0x3800, v0
	v_lshl_add_u64 v[24:25], v[24:25], 0, s[10:11]
	v_readlane_b32 s10, v228, 0
	s_mov_b32 s71, 0
	v_lshlrev_b32_e32 v54, 2, v1
	v_cmp_eq_u32_e64 s[0:1], 3, v21
	v_cmp_eq_u32_e64 s[4:5], 2, v21
	v_cmp_eq_u32_e64 s[6:7], 1, v21
	v_cmp_ne_u32_e64 s[8:9], 0, v21
	v_or_b32_e32 v56, 64, v20
	v_or_b32_e32 v57, 1, v20
	v_or_b32_e32 v58, 0x41, v20
	v_or_b32_e32 v59, 2, v20
	v_or_b32_e32 v60, 0x42, v20
	v_or_b32_e32 v61, 3, v20
	v_or_b32_e32 v62, 0x43, v20
	v_or_b32_e32 v63, 16, v20
	v_or_b32_e32 v64, 0x50, v20
	v_or_b32_e32 v65, 17, v20
	v_or_b32_e32 v66, 0x51, v20
	v_or_b32_e32 v67, 18, v20
	v_or_b32_e32 v68, 0x52, v20
	v_or_b32_e32 v69, 19, v20
	v_or_b32_e32 v70, 0x53, v20
	v_or_b32_e32 v71, 32, v20
	v_or_b32_e32 v72, 0x60, v20
	v_or_b32_e32 v73, 33, v20
	v_or_b32_e32 v74, 0x61, v20
	v_or_b32_e32 v75, 34, v20
	v_or_b32_e32 v76, 0x62, v20
	v_or_b32_e32 v77, 35, v20
	v_or_b32_e32 v78, 0x63, v20
	v_or_b32_e32 v79, 48, v20
	v_or_b32_e32 v80, 0x70, v20
	v_or_b32_e32 v81, 49, v20
	v_or_b32_e32 v82, 0x71, v20
	v_or_b32_e32 v83, 50, v20
	v_or_b32_e32 v84, 0x72, v20
	v_or_b32_e32 v85, 51, v20
	v_or_b32_e32 v86, 0x73, v20
	v_or_b32_e32 v87, 1, v55
	v_or_b32_e32 v88, 2, v55
	v_or_b32_e32 v89, 3, v55
	v_or_b32_e32 v90, 4, v55
	v_or_b32_e32 v91, 5, v55
	v_or_b32_e32 v92, 6, v55
	v_or_b32_e32 v93, 7, v55
	v_or_b32_e32 v94, 8, v55
	v_or_b32_e32 v95, 9, v55
	v_or_b32_e32 v96, 10, v55
	v_or_b32_e32 v97, 11, v55
	v_or_b32_e32 v98, 12, v55
	v_or_b32_e32 v99, 13, v55
	v_or_b32_e32 v100, 14, v55
	v_or_b32_e32 v101, 15, v55
	v_or_b32_e32 v102, 31, v55
	v_or_b32_e32 v103, 30, v55
	v_or_b32_e32 v104, 29, v55
	v_or_b32_e32 v105, 28, v55
	v_or_b32_e32 v106, 27, v55
	v_or_b32_e32 v107, 26, v55
	v_or_b32_e32 v108, 25, v55
	v_or_b32_e32 v109, 24, v55
	v_or_b32_e32 v110, 23, v55
	v_or_b32_e32 v111, 22, v55
	v_or_b32_e32 v112, 21, v55
	v_or_b32_e32 v113, 20, v55
	v_or_b32_e32 v114, 19, v55
	v_or_b32_e32 v115, 18, v55
	v_or_b32_e32 v116, 17, v55
	v_or_b32_e32 v117, 16, v55
	v_or_b32_e32 v118, 47, v55
	v_or_b32_e32 v119, 46, v55
	v_or_b32_e32 v120, 45, v55
	v_or_b32_e32 v121, 44, v55
	v_or_b32_e32 v122, 43, v55
	v_or_b32_e32 v123, 42, v55
	v_or_b32_e32 v124, 41, v55
	v_or_b32_e32 v125, 40, v55
	v_or_b32_e32 v126, 39, v55
	v_or_b32_e32 v127, 38, v55
	v_or_b32_e32 v128, 37, v55
	v_or_b32_e32 v129, 36, v55
	v_or_b32_e32 v130, 35, v55
	v_or_b32_e32 v131, 34, v55
	v_or_b32_e32 v132, 33, v55
	v_or_b32_e32 v133, 32, v55
	v_or_b32_e32 v134, 63, v55
	v_or_b32_e32 v135, 55, v55
	v_or_b32_e32 v136, 59, v55
	v_or_b32_e32 v137, 51, v55
	v_or_b32_e32 v138, 61, v55
	v_or_b32_e32 v139, 53, v55
	v_or_b32_e32 v140, 57, v55
	v_or_b32_e32 v141, 49, v55
	v_or_b32_e32 v142, 62, v55
	v_or_b32_e32 v143, 54, v55
	v_or_b32_e32 v144, 58, v55
	v_or_b32_e32 v145, 50, v55
	v_or_b32_e32 v146, 60, v55
	v_or_b32_e32 v147, 52, v55
	v_or_b32_e32 v148, 56, v55
	v_or_b32_e32 v149, 48, v55
	v_lshlrev_b32_e32 v26, 1, v2
	v_mov_b32_e32 v27, v19
	v_lshlrev_b32_e32 v28, 1, v0
	v_mov_b32_e32 v29, v19
	v_lshlrev_b32_e32 v30, 1, v4
	v_mov_b32_e32 v31, v19
	v_lshlrev_b32_e32 v32, 1, v6
	v_mov_b32_e32 v33, v19
	v_lshlrev_b32_e32 v34, 1, v8
	v_mov_b32_e32 v35, v19
	v_lshlrev_b32_e32 v36, 1, v10
	v_mov_b32_e32 v37, v19
	v_lshlrev_b32_e32 v38, 1, v12
	v_mov_b32_e32 v39, v19
	v_lshlrev_b32_e32 v40, 1, v14
	v_mov_b32_e32 v41, v19
	v_lshlrev_b32_e32 v42, 1, v42
	v_mov_b32_e32 v43, v19
	s_mov_b64 s[72:73], 0x80
	s_mov_b64 s[76:77], 0xc0
	s_movk_i32 s33, 0xff80
	s_brev_b32 s75, -2
	s_movk_i32 s80, 0x7f
	v_add_u32_e32 v150, v49, v18
	s_movk_i32 s81, 0xff00
	v_mov_b32_e32 v151, 0x7fffff80
	v_mov_b32_e32 v152, 0x7fffff00
	s_mov_b32 s82, s10
	v_readlane_b32 s11, v228, 1
	s_branch .LBB0_758

; __device__ __forceinline__ f32x4 mfma16(bf16x8 a, bf16x8 b, f32x4 c) { return __builtin_amdgcn_mfma_f32_16x16x32_bf16(a, b, c, 0, 0, 0); }
; __device__ void ph_score(const P& p, int* lds) {
;     ...
; #pragma unroll
;     for (int half = 0; half < 2; ++half) {
;       const u16* Kb = (half ? p_K2b : p_K1b) + h * 128 * 128;
;       f32x4 sc[8];
; #pragma unroll
;       for (int mt = 0; mt < 8; ++mt) sc[mt] = f32x4{0.f, 0.f, 0.f, 0.f};
; #pragma unroll
;       for (int ks = 0; ks < 4; ++ks) {
;         bf16x8 qf = *(const bf16x8*)(Qb + tok * 2048 + h * 256 + half * 128 + ks * 32 + fq * 8);
; #pragma unroll
;         for (int mt = 0; mt < 8; ++mt) {
;           bf16x8 kf = *(const bf16x8*)(Kb + (mt * 16 + fr) * 128 + ks * 32 + fq * 8);
;           sc[mt] = mfma16(kf, qf, sc[mt]);
;         }
;       }
.LBB0_758:
	s_and_b32 s86, s82, 7
	s_cmp_eq_u32 s86, s87
	s_cbranch_scc1 .Lsc_keys_ok
	s_mov_b32 s87, s86
	s_waitcnt lgkmcnt(0)
	s_barrier
	v_readlane_b32 s88, v228, 8
	v_readlane_b32 s89, v228, 9
	s_lshl_b32 s86, s86, 15
	s_add_u32 s88, s88, 0xe40000
	s_addc_u32 s89, s89, 0
	s_add_u32 s88, s88, s86
	s_addc_u32 s89, s89, 0
	s_mov_b32 s90, s88
	v_lshlrev_b32_e32 v218, 4, v220
	v_lshrrev_b32_e32 v219, 4, v220
	v_and_b32_e32 v221, 15, v220
	v_mul_u32_u24_e32 v219, 0x110, v219
	v_lshl_add_u32 v219, v221, 4, v219
	v_add_u32_e32 v222, 0x8000, v219
	global_load_dwordx4 v[154:157], v218, s[88:89]
	s_add_u32 s88, s88, 0x1000
	s_addc_u32 s89, s89, 0
	global_load_dwordx4 v[158:161], v218, s[88:89]
	s_add_u32 s88, s88, 0x1000
	s_addc_u32 s89, s89, 0
	global_load_dwordx4 v[162:165], v218, s[88:89]
	s_add_u32 s88, s88, 0x1000
	s_addc_u32 s89, s89, 0
	global_load_dwordx4 v[166:169], v218, s[88:89]
	s_add_u32 s88, s88, 0x1000
	s_addc_u32 s89, s89, 0
	global_load_dwordx4 v[170:173], v218, s[88:89]
	s_add_u32 s88, s88, 0x1000
	s_addc_u32 s89, s89, 0
	global_load_dwordx4 v[174:177], v218, s[88:89]
	s_add_u32 s88, s88, 0x1000
	s_addc_u32 s89, s89, 0
	global_load_dwordx4 v[178:181], v218, s[88:89]
	s_add_u32 s88, s88, 0x1000
	s_addc_u32 s89, s89, 0
	global_load_dwordx4 v[182:185], v218, s[88:89]
	s_add_u32 s88, s88, 0x39000
	s_addc_u32 s89, s89, 0
	global_load_dwordx4 v[186:189], v218, s[88:89]
	s_add_u32 s88, s88, 0x1000
	s_addc_u32 s89, s89, 0
	global_load_dwordx4 v[190:193], v218, s[88:89]
	s_add_u32 s88, s88, 0x1000
	s_addc_u32 s89, s89, 0
	global_load_dwordx4 v[194:197], v218, s[88:89]
	s_add_u32 s88, s88, 0x1000
	s_addc_u32 s89, s89, 0
	global_load_dwordx4 v[198:201], v218, s[88:89]
	s_add_u32 s88, s88, 0x1000
	s_addc_u32 s89, s89, 0
	global_load_dwordx4 v[202:205], v218, s[88:89]
	s_add_u32 s88, s88, 0x1000
	s_addc_u32 s89, s89, 0
	global_load_dwordx4 v[206:209], v218, s[88:89]
	s_add_u32 s88, s88, 0x1000
	s_addc_u32 s89, s89, 0
	global_load_dwordx4 v[210:213], v218, s[88:89]
	s_add_u32 s88, s88, 0x1000
	s_addc_u32 s89, s89, 0
	global_load_dwordx4 v[214:217], v218, s[88:89]
	s_waitcnt vmcnt(0)
	ds_write_b128 v219, v[154:157] offset:8192
	ds_write_b128 v219, v[158:161] offset:12544
	ds_write_b128 v219, v[162:165] offset:16896
	ds_write_b128 v219, v[166:169] offset:21248
	ds_write_b128 v219, v[170:173] offset:25600
	ds_write_b128 v219, v[174:177] offset:29952
	ds_write_b128 v219, v[178:181] offset:34304
	ds_write_b128 v219, v[182:185] offset:38656
	ds_write_b128 v222, v[186:189] offset:10448
	ds_write_b128 v222, v[190:193] offset:14800
	ds_write_b128 v222, v[194:197] offset:19152
	ds_write_b128 v222, v[198:201] offset:23504
	ds_write_b128 v222, v[202:205] offset:27856
	ds_write_b128 v222, v[206:209] offset:32208
	ds_write_b128 v222, v[210:213] offset:36560
	ds_write_b128 v222, v[214:217] offset:40912
	s_waitcnt lgkmcnt(0)
	s_barrier
	s_mov_b32 s84, s90
	s_add_u32 s85, s90, 0x40000
